# early L1 invalidate in grid barriers + next phase's kernarg pointer loads issued before the closing workgroup barrier
# speedup vs baseline: 1.0049x; 1.0049x over previous
; #define PP (kp_get())
; DI void xcd_barrier(const XcdBarrier& b) {
;     ...
;     }
;     __syncthreads();
; __global__ void __launch_bounds__(512, 2) fwd_megakernel(Params P) {
;     ...
;         { pg8::Gemm g{HBUF, (const bf16_t*)(PP->ws + WS_WIN), DM, DM, DM, 0, 0}; pg8::SchedMN S{MTOK / 256, NINA / 256, G, c};
;           pg8::EpiInProj E{PP->ws, (const f32x2_t*)(PP->ws + WS_ROPE), (const float*)(PP->ws + WS_PART)}; pg8::gemm_phase(lds, g, S, E); }
.LBB0_175:
	s_or_b64 exec, exec, s[30:31]
	s_mov_b64 s[12:13], s[0:1]
	s_waitcnt lgkmcnt(0)
	s_load_dwordx2 s[36:37], s[12:13], 0xe0
	s_mov_b64 s[12:13], s[0:1]
	s_load_dwordx2 s[44:45], s[12:13], 0xe0
	s_mov_b64 s[12:13], s[0:1]
	s_load_dwordx2 s[62:63], s[12:13], 0xe0
	s_mov_b64 s[12:13], s[0:1]
	s_load_dwordx2 s[30:31], s[12:13], 0xe0
	s_mov_b64 s[12:13], s[0:1]
	s_load_dwordx2 s[38:39], s[12:13], 0xe0
	s_barrier
	v_readlane_b32 s12, v252, 16
	v_readlane_b32 s13, v252, 17
	v_mov_b32_e32 v0, v196
	s_andn2_b64 vcc, exec, s[12:13]
	v_cndmask_b32_e64 v2, 0, 1, s[12:13]
	v_cmp_ne_u32_e64 s[68:69], 1, v2
	v_readfirstlane_b32 s14, v0
	s_cbranch_vccnz .LBB0_177
	v_readlane_b32 s12, v253, 41
	s_mov_b32 s64, s12
	v_readlane_b32 s12, v253, 40
	s_mov_b32 s66, s12

; #define PP (kp_get())
; DI void xcd_barrier(const XcdBarrier& b) {
;     ...
;     }
;     __syncthreads();
; __global__ void __launch_bounds__(512, 2) fwd_megakernel(Params P) {
;     ...
;         { pg8::GmArgs ga{HBUF, (const bf16_t*)(PP->ws + WS_WIN) + (size_t)NINA * DM, (const bf16_t*)(PP->ws + WS_YSSM), (long)(WS_SQ - WS_YSSM) / 2, (const bf16_t*)(PP->ws + WS_WB),
;                          (bf16_t*)(PP->ws + WS_GS), (bf16_t*)(PP->ws + WS_H2), (const float*)(PP->ws + WS_PART)};
;           pg8::SchedGM S{MTOK / 256, 4, G, c}; pg8::gemm_phase_gm(lds, ga, S); }
.LBB0_798:
	s_or_b64 exec, exec, s[30:31]
	s_mov_b64 s[12:13], s[0:1]
	s_waitcnt lgkmcnt(0)
	s_load_dwordx2 s[62:63], s[12:13], 0xe0
	s_mov_b64 s[12:13], s[0:1]
	s_load_dwordx2 s[64:65], s[12:13], 0xe0
	s_mov_b64 s[12:13], s[0:1]
	s_load_dwordx2 s[36:37], s[12:13], 0xe0
	s_mov_b64 s[12:13], s[0:1]
	s_load_dwordx2 s[44:45], s[12:13], 0xe0
	s_mov_b64 s[12:13], s[0:1]
	s_load_dwordx2 s[30:31], s[12:13], 0xe0
	s_mov_b64 s[12:13], s[0:1]
	s_load_dwordx2 s[50:51], s[12:13], 0xe0
	s_mov_b64 s[12:13], s[0:1]
	s_load_dwordx2 s[38:39], s[12:13], 0xe0
	s_barrier
	v_readlane_b32 s12, v252, 28
	v_mov_b32_e32 v6, v196
	v_readlane_b32 s13, v252, 29
	s_and_b64 vcc, exec, s[12:13]
	v_readfirstlane_b32 s13, v6
	s_cbranch_vccnz .LBB0_800
	v_readlane_b32 s14, v253, 55
	v_readlane_b32 s52, v253, 51
	s_mov_b32 s49, s14
	v_readlane_b32 s53, v253, 52
	v_readlane_b32 s15, v253, 56

; #define PP (kp_get())
; DI void xcd_barrier(const XcdBarrier& b) {
;     ...
;     }
;     __syncthreads();
; __global__ void __launch_bounds__(512, 2) fwd_megakernel(Params P) {
;     ...
;         { pg8::Gemm g{(const bf16_t*)(PP->ws + WS_H2), (const bf16_t*)(PP->ws + WS_WOUT), DM, DM, DM, 0, 0}; pg8::SchedMN S{MTOK / 256, 4, G, c}; pg8::EpiResid E{xin, PP->out, HBUF, PP->norm_cross + l * DM, (float*)(PP->ws + WS_PART)}; pg8::gemm_phase(lds, g, S, E); }
.LBB0_939:
	s_or_b64 exec, exec, s[30:31]
	s_mov_b64 s[12:13], s[0:1]
	s_waitcnt lgkmcnt(0)
	s_load_dwordx2 s[36:37], s[12:13], 0xe0
	s_mov_b64 s[12:13], s[0:1]
	s_load_dwordx2 s[38:39], s[12:13], 0xe0
	s_mov_b64 s[12:13], s[0:1]
	s_load_dwordx2 s[62:63], s[12:13], 0xd8
	s_mov_b64 s[12:13], s[0:1]
	s_load_dwordx2 s[66:67], s[12:13], 0xe0
	s_mov_b64 s[12:13], s[0:1]
	s_load_dwordx2 s[50:51], s[12:13], 0x90
	s_mov_b64 s[12:13], s[0:1]
	s_load_dwordx2 s[44:45], s[12:13], 0xe0
	s_barrier
	v_readlane_b32 s12, v252, 28
	v_mov_b32_e32 v16, v196
	v_readlane_b32 s13, v252, 29
	s_and_b64 vcc, exec, s[12:13]
	v_readfirstlane_b32 s28, v16
	s_cbranch_vccnz .LBB0_941
	v_readlane_b32 s82, v253, 55
	v_readlane_b32 s30, v253, 51
	v_readlane_b32 s83, v253, 56
	v_readlane_b32 s31, v253, 52

; #define PP (kp_get())
; DI void xcd_barrier(const XcdBarrier& b) {
;     ...
;     }
;     __syncthreads();
; __global__ void __launch_bounds__(512, 2) fwd_megakernel(Params P) {
;     ...
;         { pg8::Gemm g{HBUF, (const bf16_t*)(PP->ws + WS_WXQ), DM, DM, DM, 0, 0}; pg8::SchedMN S{MTOK / 256, 2, G, c};
;           pg8::EpiBf16<0, true> E{(bf16_t*)(PP->ws + WS_XQ), 512, 0.12751743074602334f, (const float*)(PP->ws + WS_PART)}; pg8::gemm_phase(lds, g, S, E); }
.LBB0_1029:
	s_or_b64 exec, exec, s[30:31]
	s_mov_b64 s[12:13], s[0:1]
	s_waitcnt lgkmcnt(0)
	s_load_dwordx2 s[30:31], s[12:13], 0xe0
	s_mov_b64 s[12:13], s[0:1]
	s_load_dwordx2 s[44:45], s[12:13], 0xe0
	s_mov_b64 s[12:13], s[0:1]
	s_load_dwordx2 s[36:37], s[12:13], 0xe0
	s_mov_b64 s[12:13], s[0:1]
	s_load_dwordx2 s[38:39], s[12:13], 0xe0
	s_barrier
	v_mov_b32_e32 v10, v196
	s_and_b64 vcc, exec, s[94:95]
	v_readfirstlane_b32 s49, v10
	s_cbranch_vccnz .LBB0_1031
	v_readlane_b32 s12, v253, 0
	s_mov_b32 s62, s12
	v_readlane_b32 s12, v253, 1
	s_mov_b32 s64, s12

; #define PP (kp_get())
; DI void xcd_barrier(const XcdBarrier& b) {
;     ...
;     }
;     __syncthreads();
; __global__ void __launch_bounds__(512, 2) fwd_megakernel(Params P) {
;     ...
;         { pg8::Gemm g{(const bf16_t*)(PP->ws + WS_XQ), (const bf16_t*)(PP->ws + WS_WXO), 512, 512, 512, 0, 0}; pg8::SchedMN S{MTOK / 256, 4, G, c}; pg8::EpiResid E{PP->out, PP->out, HBUF, PP->norm_mlp + l * DM, (float*)(PP->ws + WS_PART)}; pg8::gemm_phase(lds, g, S, E); }
.LBB0_1238:
	s_or_b64 exec, exec, s[30:31]
	s_mov_b64 s[12:13], s[0:1]
	s_waitcnt lgkmcnt(0)
	s_load_dwordx2 s[36:37], s[12:13], 0xe0
	s_mov_b64 s[12:13], s[0:1]
	s_load_dwordx2 s[38:39], s[12:13], 0xe0
	s_mov_b64 s[12:13], s[0:1]
	s_load_dwordx2 s[30:31], s[12:13], 0xd8
	s_mov_b64 s[12:13], s[0:1]
	s_load_dwordx2 s[48:49], s[12:13], 0xd8
	s_mov_b64 s[12:13], s[0:1]
	s_load_dwordx2 s[64:65], s[12:13], 0xe0
	s_mov_b64 s[12:13], s[0:1]
	s_load_dwordx2 s[66:67], s[12:13], 0xb8
	s_mov_b64 s[12:13], s[0:1]
	s_load_dwordx2 s[50:51], s[12:13], 0xe0
	s_barrier
	v_readlane_b32 s12, v252, 28
	v_mov_b32_e32 v16, v196
	v_readlane_b32 s13, v252, 29
	s_and_b64 vcc, exec, s[12:13]
	v_readfirstlane_b32 s28, v16
	s_cbranch_vccnz .LBB0_1240
	v_readlane_b32 s78, v253, 55
	v_readlane_b32 s44, v253, 51
	v_readlane_b32 s79, v253, 56
	v_readlane_b32 s45, v253, 52

; #define PP (kp_get())
; DI void xcd_barrier(const XcdBarrier& b) {
;     ...
;     }
;     __syncthreads();
; __global__ void __launch_bounds__(512, 2) fwd_megakernel(Params P) {
;     ...
;         { pg8::Gemm g{HBUF, (const bf16_t*)(PP->ws + WS_WUP), DM, DM, DM, 0, 0}; pg8::SchedMN S{MTOK / 256, 16, G, c};
;           pg8::EpiBf16<2, true> E{(bf16_t*)(PP->ws + WS_HID), 4096, 1.f, (const float*)(PP->ws + WS_PART)}; pg8::gemm_phase(lds, g, S, E); }
.LBB0_1328:
	s_or_b64 exec, exec, s[30:31]
	s_mov_b64 s[12:13], s[0:1]
	s_waitcnt lgkmcnt(0)
	s_load_dwordx2 s[36:37], s[12:13], 0xe0
	s_mov_b64 s[12:13], s[0:1]
	s_load_dwordx2 s[50:51], s[12:13], 0xe0
	s_mov_b64 s[12:13], s[0:1]
	s_load_dwordx2 s[44:45], s[12:13], 0xe0
	s_mov_b64 s[12:13], s[0:1]
	s_load_dwordx2 s[38:39], s[12:13], 0xe0
	s_barrier
	v_readlane_b32 s12, v252, 62
	v_readlane_b32 s13, v252, 63
	v_mov_b32_e32 v10, v196
	s_andn2_b64 vcc, exec, s[12:13]
	v_cndmask_b32_e64 v0, 0, 1, s[12:13]
	v_cmp_ne_u32_e64 s[68:69], 1, v0
	v_readfirstlane_b32 s64, v10
	s_cbranch_vccnz .LBB0_1330
	v_readlane_b32 s12, v253, 3
	s_mov_b32 s30, s12
	v_readlane_b32 s12, v253, 4
	s_mov_b32 s48, s12

; #define PP (kp_get())
; DI void xcd_barrier(const XcdBarrier& b) {
;     ...
;     }
;     __syncthreads();
; __global__ void __launch_bounds__(512, 2) fwd_megakernel(Params P) {
;     ...
;         { pg8::Gemm g{(const bf16_t*)(PP->ws + WS_HID), (const bf16_t*)(PP->ws + WS_WDN), 4096, 4096, 4096, 0, 0}; pg8::SchedMN S{MTOK / 256, 4, G, c}; pg8::EpiResid E{PP->out, PP->out, HBUF, PP->norm_mix + (l + 1 < DEPTH ? l + 1 : l) * DM, (float*)(PP->ws + WS_PART)}; pg8::gemm_phase(lds, g, S, E); }
.LBB0_1425:
	s_or_b64 exec, exec, s[30:31]
	s_mov_b64 s[12:13], s[0:1]
	s_waitcnt lgkmcnt(0)
	s_load_dwordx2 s[36:37], s[12:13], 0xe0
	s_mov_b64 s[12:13], s[0:1]
	s_load_dwordx2 s[38:39], s[12:13], 0xe0
	s_mov_b64 s[12:13], s[0:1]
	s_load_dwordx2 s[30:31], s[12:13], 0xd8
	s_mov_b64 s[12:13], s[0:1]
	s_load_dwordx2 s[48:49], s[12:13], 0xd8
	s_mov_b64 s[12:13], s[0:1]
	s_load_dwordx2 s[62:63], s[12:13], 0xe0
	s_mov_b64 s[12:13], s[0:1]
	s_load_dwordx2 s[64:65], s[12:13], 0x18
	s_mov_b64 s[12:13], s[0:1]
	s_load_dwordx2 s[50:51], s[12:13], 0xe0
	s_barrier
	v_readlane_b32 s12, v252, 28
	v_mov_b32_e32 v16, v196
	v_readlane_b32 s13, v252, 29
	s_and_b64 vcc, exec, s[12:13]
	v_readfirstlane_b32 s28, v16
	s_cbranch_vccnz .LBB0_1427
	v_readlane_b32 s78, v253, 55
	v_readlane_b32 s44, v253, 51
	v_readlane_b32 s79, v253, 56
	v_readlane_b32 s45, v253, 52
